# combo10 + accumulator zeroing at unit head via 64 v_mov_b64 instead of 128 v_mov_b32 (UP, IN, EG, PL)
# speedup vs baseline: 1.0070x; 1.0022x over previous
; template <class Epi, class Sched, bool ALIGN_EPI = false, bool SP2 = false, bool ACHUNK = false>
; __device__ __forceinline__ void gemm_phase(PG8_LAS unsigned char* lds, const Gemm g, const Sched& S, const Epi& E) {
;     ...
;         for (int a = 0; a < 2; ++a)
; #pragma unroll
;             for (int b = 0; b < 2; ++b)
; #pragma unroll
;                 for (int m = 0; m < 4; ++m)
; #pragma unroll
;                     for (int n = 0; n < 2; ++n) acc[a][b][m][n] = (f32x4){0.f, 0.f, 0.f, 0.f};
;         }
.LBB0_106:
	s_andn2_b64 vcc, exec, s[44:45]
	s_nop 0
	s_cbranch_vccnz .LBB0_110
	s_add_u32 s8, s4, 0x100
	s_addc_u32 s9, s5, 0
	s_add_u32 s0, s6, 0x80
	v_mov_b64_e32 v[4:5], 0
	s_addc_u32 s1, s7, 0
	s_mov_b32 s4, 0
	v_mov_b64_e32 v[6:7], 0
	v_mov_b64_e32 v[8:9], 0
	v_mov_b64_e32 v[10:11], 0
	v_mov_b64_e32 v[12:13], 0
	v_mov_b64_e32 v[14:15], 0
	v_mov_b64_e32 v[16:17], 0
	v_mov_b64_e32 v[18:19], 0
	v_mov_b64_e32 v[24:25], 0
	v_mov_b64_e32 v[26:27], 0
	v_mov_b64_e32 v[20:21], 0
	v_mov_b64_e32 v[22:23], 0
	v_mov_b64_e32 v[32:33], 0
	v_mov_b64_e32 v[34:35], 0
	v_mov_b64_e32 v[28:29], 0
	v_mov_b64_e32 v[30:31], 0
	v_mov_b64_e32 v[68:69], 0
	v_mov_b64_e32 v[70:71], 0
	v_mov_b64_e32 v[72:73], 0
	v_mov_b64_e32 v[74:75], 0
	v_mov_b64_e32 v[76:77], 0
	v_mov_b64_e32 v[78:79], 0
	v_mov_b64_e32 v[80:81], 0
	v_mov_b64_e32 v[82:83], 0
	v_mov_b64_e32 v[84:85], 0
	v_mov_b64_e32 v[86:87], 0
	v_mov_b64_e32 v[88:89], 0
	v_mov_b64_e32 v[90:91], 0
	v_mov_b64_e32 v[92:93], 0
	v_mov_b64_e32 v[94:95], 0
	v_mov_b64_e32 v[96:97], 0
	v_mov_b64_e32 v[98:99], 0
	v_mov_b64_e32 v[100:101], 0
	v_mov_b64_e32 v[102:103], 0
	v_mov_b64_e32 v[104:105], 0
	v_mov_b64_e32 v[106:107], 0
	v_mov_b64_e32 v[108:109], 0
	v_mov_b64_e32 v[110:111], 0
	v_mov_b64_e32 v[112:113], 0
	v_mov_b64_e32 v[114:115], 0
	v_mov_b64_e32 v[120:121], 0
	v_mov_b64_e32 v[122:123], 0
	v_mov_b64_e32 v[116:117], 0
	v_mov_b64_e32 v[118:119], 0
	v_mov_b64_e32 v[128:129], 0
	v_mov_b64_e32 v[130:131], 0
	v_mov_b64_e32 v[124:125], 0
	v_mov_b64_e32 v[126:127], 0
	v_mov_b64_e32 v[156:157], 0
	v_mov_b64_e32 v[158:159], 0
	v_mov_b64_e32 v[160:161], 0
	v_mov_b64_e32 v[162:163], 0
	v_mov_b64_e32 v[144:145], 0
	v_mov_b64_e32 v[146:147], 0
	v_mov_b64_e32 v[136:137], 0
	v_mov_b64_e32 v[138:139], 0
	v_mov_b64_e32 v[140:141], 0
	v_mov_b64_e32 v[142:143], 0
	v_mov_b64_e32 v[132:133], 0
	v_mov_b64_e32 v[134:135], 0
	v_mov_b64_e32 v[152:153], 0
	v_mov_b64_e32 v[154:155], 0
	v_mov_b64_e32 v[148:149], 0
	v_mov_b64_e32 v[150:151], 0

; template <class Epi, class Sched, bool ALIGN_EPI = false, bool SP2 = false, bool ACHUNK = false>
; __device__ __forceinline__ void gemm_phase(PG8_LAS unsigned char* lds, const Gemm g, const Sched& S, const Epi& E) {
;     ...
;         for (int a = 0; a < 2; ++a)
; #pragma unroll
;             for (int b = 0; b < 2; ++b)
; #pragma unroll
;                 for (int m = 0; m < 4; ++m)
; #pragma unroll
;                     for (int n = 0; n < 2; ++n) acc[a][b][m][n] = (f32x4){0.f, 0.f, 0.f, 0.f};
;         }
.LBB0_351:
	s_andn2_b64 vcc, exec, s[4:5]
	s_cbranch_vccnz .LBB0_342
	s_add_u32 s40, s18, 0x100
	s_addc_u32 s41, s19, 0
	s_add_u32 s18, s20, 0x80
	v_mov_b64_e32 v[4:5], 0
	s_addc_u32 s19, s21, 0
	s_mov_b32 s20, 0
	v_mov_b64_e32 v[6:7], 0
	v_mov_b64_e32 v[8:9], 0
	v_mov_b64_e32 v[10:11], 0
	v_mov_b64_e32 v[20:21], 0
	v_mov_b64_e32 v[22:23], 0
	v_mov_b64_e32 v[24:25], 0
	v_mov_b64_e32 v[26:27], 0
	v_mov_b64_e32 v[36:37], 0
	v_mov_b64_e32 v[38:39], 0
	v_mov_b64_e32 v[40:41], 0
	v_mov_b64_e32 v[42:43], 0
	v_mov_b64_e32 v[52:53], 0
	v_mov_b64_e32 v[54:55], 0
	v_mov_b64_e32 v[56:57], 0
	v_mov_b64_e32 v[58:59], 0
	v_mov_b64_e32 v[12:13], 0
	v_mov_b64_e32 v[14:15], 0
	v_mov_b64_e32 v[16:17], 0
	v_mov_b64_e32 v[18:19], 0
	v_mov_b64_e32 v[28:29], 0
	v_mov_b64_e32 v[30:31], 0
	v_mov_b64_e32 v[32:33], 0
	v_mov_b64_e32 v[34:35], 0
	v_mov_b64_e32 v[44:45], 0
	v_mov_b64_e32 v[46:47], 0
	v_mov_b64_e32 v[48:49], 0
	v_mov_b64_e32 v[50:51], 0
	v_mov_b64_e32 v[60:61], 0
	v_mov_b64_e32 v[62:63], 0
	v_mov_b64_e32 v[64:65], 0
	v_mov_b64_e32 v[66:67], 0
	v_mov_b64_e32 v[68:69], 0
	v_mov_b64_e32 v[70:71], 0
	v_mov_b64_e32 v[72:73], 0
	v_mov_b64_e32 v[74:75], 0
	v_mov_b64_e32 v[84:85], 0
	v_mov_b64_e32 v[86:87], 0
	v_mov_b64_e32 v[88:89], 0
	v_mov_b64_e32 v[90:91], 0
	v_mov_b64_e32 v[100:101], 0
	v_mov_b64_e32 v[102:103], 0
	v_mov_b64_e32 v[104:105], 0
	v_mov_b64_e32 v[106:107], 0
	v_mov_b64_e32 v[116:117], 0
	v_mov_b64_e32 v[118:119], 0
	v_mov_b64_e32 v[120:121], 0
	v_mov_b64_e32 v[122:123], 0
	v_mov_b64_e32 v[76:77], 0
	v_mov_b64_e32 v[78:79], 0
	v_mov_b64_e32 v[80:81], 0
	v_mov_b64_e32 v[82:83], 0
	v_mov_b64_e32 v[92:93], 0
	v_mov_b64_e32 v[94:95], 0
	v_mov_b64_e32 v[96:97], 0
	v_mov_b64_e32 v[98:99], 0
	v_mov_b64_e32 v[108:109], 0
	v_mov_b64_e32 v[110:111], 0
	v_mov_b64_e32 v[112:113], 0
	v_mov_b64_e32 v[114:115], 0
	v_mov_b64_e32 v[128:129], 0
	v_mov_b64_e32 v[130:131], 0
	v_mov_b64_e32 v[124:125], 0
	v_mov_b64_e32 v[126:127], 0

; template <class Epi, class Sched, bool ALIGN_EPI = false, bool SP2 = false, bool ACHUNK = false>
; __device__ __forceinline__ void gemm_phase(PG8_LAS unsigned char* lds, const Gemm g, const Sched& S, const Epi& E) {
;     ...
;         for (int a = 0; a < 2; ++a)
; #pragma unroll
;             for (int b = 0; b < 2; ++b)
; #pragma unroll
;                 for (int m = 0; m < 4; ++m)
; #pragma unroll
;                     for (int n = 0; n < 2; ++n) acc[a][b][m][n] = (f32x4){0.f, 0.f, 0.f, 0.f};
;         }
.LBB0_375:
	s_andn2_b64 vcc, exec, s[34:35]
	s_cbranch_vccnz .LBB0_379
	s_add_u32 s4, s4, 0x80
	s_addc_u32 s5, s5, 0
	s_add_u32 s8, s6, 0x100
	v_mov_b64_e32 v[8:9], 0
	s_addc_u32 s9, s7, 0
	s_mov_b32 s6, 0
	v_mov_b64_e32 v[10:11], 0
	v_mov_b64_e32 v[16:17], 0
	v_mov_b64_e32 v[18:19], 0
	v_mov_b64_e32 v[24:25], 0
	v_mov_b64_e32 v[26:27], 0
	v_mov_b64_e32 v[32:33], 0
	v_mov_b64_e32 v[34:35], 0
	v_mov_b64_e32 v[40:41], 0
	v_mov_b64_e32 v[42:43], 0
	v_mov_b64_e32 v[48:49], 0
	v_mov_b64_e32 v[50:51], 0
	v_mov_b64_e32 v[56:57], 0
	v_mov_b64_e32 v[58:59], 0
	v_mov_b64_e32 v[64:65], 0
	v_mov_b64_e32 v[66:67], 0
	v_mov_b64_e32 v[4:5], 0
	v_mov_b64_e32 v[6:7], 0
	v_mov_b64_e32 v[12:13], 0
	v_mov_b64_e32 v[14:15], 0
	v_mov_b64_e32 v[20:21], 0
	v_mov_b64_e32 v[22:23], 0
	v_mov_b64_e32 v[28:29], 0
	v_mov_b64_e32 v[30:31], 0
	v_mov_b64_e32 v[36:37], 0
	v_mov_b64_e32 v[38:39], 0
	v_mov_b64_e32 v[44:45], 0
	v_mov_b64_e32 v[46:47], 0
	v_mov_b64_e32 v[52:53], 0
	v_mov_b64_e32 v[54:55], 0
	v_mov_b64_e32 v[60:61], 0
	v_mov_b64_e32 v[62:63], 0
	v_mov_b64_e32 v[72:73], 0
	v_mov_b64_e32 v[74:75], 0
	v_mov_b64_e32 v[80:81], 0
	v_mov_b64_e32 v[82:83], 0
	v_mov_b64_e32 v[88:89], 0
	v_mov_b64_e32 v[90:91], 0
	v_mov_b64_e32 v[96:97], 0
	v_mov_b64_e32 v[98:99], 0
	v_mov_b64_e32 v[104:105], 0
	v_mov_b64_e32 v[106:107], 0
	v_mov_b64_e32 v[112:113], 0
	v_mov_b64_e32 v[114:115], 0
	v_mov_b64_e32 v[120:121], 0
	v_mov_b64_e32 v[122:123], 0
	v_mov_b64_e32 v[128:129], 0
	v_mov_b64_e32 v[130:131], 0
	v_mov_b64_e32 v[68:69], 0
	v_mov_b64_e32 v[70:71], 0
	v_mov_b64_e32 v[76:77], 0
	v_mov_b64_e32 v[78:79], 0
	v_mov_b64_e32 v[84:85], 0
	v_mov_b64_e32 v[86:87], 0
	v_mov_b64_e32 v[92:93], 0
	v_mov_b64_e32 v[94:95], 0
	v_mov_b64_e32 v[100:101], 0
	v_mov_b64_e32 v[102:103], 0
	v_mov_b64_e32 v[108:109], 0
	v_mov_b64_e32 v[110:111], 0
	v_mov_b64_e32 v[116:117], 0
	v_mov_b64_e32 v[118:119], 0
	v_mov_b64_e32 v[124:125], 0
	v_mov_b64_e32 v[126:127], 0

; template <class Epi, class Sched, bool ALIGN_EPI = false, bool SP2 = false, bool ACHUNK = false>
; __device__ __forceinline__ void gemm_phase(PG8_LAS unsigned char* lds, const Gemm g, const Sched& S, const Epi& E) {
;     ...
;         for (int a = 0; a < 2; ++a)
; #pragma unroll
;             for (int b = 0; b < 2; ++b)
; #pragma unroll
;                 for (int m = 0; m < 4; ++m)
; #pragma unroll
;                     for (int n = 0; n < 2; ++n) acc[a][b][m][n] = (f32x4){0.f, 0.f, 0.f, 0.f};
;         }
.LBB0_429:
	s_andn2_b64 vcc, exec, s[54:55]
	s_nop 0
	s_cbranch_vccnz .LBB0_432
	s_add_u32 s0, s6, 0x80
	s_addc_u32 s1, s7, 0
	s_add_u32 s6, s4, 0x100
	v_mov_b64_e32 v[4:5], 0
	s_addc_u32 s7, s5, 0
	s_mov_b32 s4, 0
	v_mov_b64_e32 v[6:7], 0
	v_mov_b64_e32 v[8:9], 0
	v_mov_b64_e32 v[10:11], 0
	v_mov_b64_e32 v[20:21], 0
	v_mov_b64_e32 v[22:23], 0
	v_mov_b64_e32 v[24:25], 0
	v_mov_b64_e32 v[26:27], 0
	v_mov_b64_e32 v[36:37], 0
	v_mov_b64_e32 v[38:39], 0
	v_mov_b64_e32 v[40:41], 0
	v_mov_b64_e32 v[42:43], 0
	v_mov_b64_e32 v[52:53], 0
	v_mov_b64_e32 v[54:55], 0
	v_mov_b64_e32 v[56:57], 0
	v_mov_b64_e32 v[58:59], 0
	v_mov_b64_e32 v[12:13], 0
	v_mov_b64_e32 v[14:15], 0
	v_mov_b64_e32 v[16:17], 0
	v_mov_b64_e32 v[18:19], 0
	v_mov_b64_e32 v[28:29], 0
	v_mov_b64_e32 v[30:31], 0
	v_mov_b64_e32 v[32:33], 0
	v_mov_b64_e32 v[34:35], 0
	v_mov_b64_e32 v[44:45], 0
	v_mov_b64_e32 v[46:47], 0
	v_mov_b64_e32 v[48:49], 0
	v_mov_b64_e32 v[50:51], 0
	v_mov_b64_e32 v[60:61], 0
	v_mov_b64_e32 v[62:63], 0
	v_mov_b64_e32 v[64:65], 0
	v_mov_b64_e32 v[66:67], 0
	v_mov_b64_e32 v[68:69], 0
	v_mov_b64_e32 v[70:71], 0
	v_mov_b64_e32 v[72:73], 0
	v_mov_b64_e32 v[74:75], 0
	v_mov_b64_e32 v[84:85], 0
	v_mov_b64_e32 v[86:87], 0
	v_mov_b64_e32 v[88:89], 0
	v_mov_b64_e32 v[90:91], 0
	v_mov_b64_e32 v[100:101], 0
	v_mov_b64_e32 v[102:103], 0
	v_mov_b64_e32 v[104:105], 0
	v_mov_b64_e32 v[106:107], 0
	v_mov_b64_e32 v[116:117], 0
	v_mov_b64_e32 v[118:119], 0
	v_mov_b64_e32 v[120:121], 0
	v_mov_b64_e32 v[122:123], 0
	v_mov_b64_e32 v[76:77], 0
	v_mov_b64_e32 v[78:79], 0
	v_mov_b64_e32 v[80:81], 0
	v_mov_b64_e32 v[82:83], 0
	v_mov_b64_e32 v[92:93], 0
	v_mov_b64_e32 v[94:95], 0
	v_mov_b64_e32 v[96:97], 0
	v_mov_b64_e32 v[98:99], 0
	v_mov_b64_e32 v[108:109], 0
	v_mov_b64_e32 v[110:111], 0
	v_mov_b64_e32 v[112:113], 0
	v_mov_b64_e32 v[114:115], 0
	v_mov_b64_e32 v[124:125], 0
	v_mov_b64_e32 v[126:127], 0
	v_mov_b64_e32 v[128:129], 0
	v_mov_b64_e32 v[130:131], 0
